# S5 pass-1 input product B*u moved from VALU pk_fma+readlane to f32 MFMA 32x32x2, with next-job prefetch
# speedup vs baseline: 1.0134x; 1.0134x over previous
; template <bool FINAL>
; __device__ __forceinline__ void s5_wave(const Params& P, int j, int g, int idx0, int stride, char* ldsw) {
;     ...
;   const float lr = P.in[I_S5LRE][jg * 64 + p], li = P.in[I_S5LIM][jg * 64 + p];
;   const float dt = expf(P.in[I_S5LOGDT][jg]);
;   const float er = expf(lr * dt);
;   float sn, cs;
;   sincosf(li * dt, &sn, &cs);
;   const float lbr = er * cs, lbi = er * sn;
;   const float nr = lbr - 1.f, ni = lbi;
;   const float den = 1.f / (lr * lr + li * li);
;   const float cr = (nr * lr + ni * li) * den, ci = (ni * lr - nr * li) * den;
;   typedef float f32x2 __attribute__((ext_vector_type(2)));
;   f32x2 bb[16];
;   {
;     const float4* br4 = reinterpret_cast<const float4*>(P.in[I_S5BRE] + ((size_t)jg * 64 + p) * 16);
;     const float4* bi4 = reinterpret_cast<const float4*>(P.in[I_S5BIM] + ((size_t)jg * 64 + p) * 16);
; #pragma unroll
;     for (int q = 0; q < 4; ++q) {
;       float4 a = br4[q], c = bi4[q];
;       bb[4 * q + 0] = (f32x2){cr * a.x - ci * c.x, cr * c.x + ci * a.x};
;       bb[4 * q + 1] = (f32x2){cr * a.y - ci * c.y, cr * c.y + ci * a.y};
;       bb[4 * q + 2] = (f32x2){cr * a.z - ci * c.z, cr * c.z + ci * a.z};
;       bb[4 * q + 3] = (f32x2){cr * a.w - ci * c.w, cr * c.w + ci * a.w};
;     }
;   }
.LBB0_520:
	s_waitcnt vmcnt(0)
	v_mul_f32_e32 v2, v36, v2
	v_mul_f32_e32 v5, 0x3fb8aa3b, v2
	s_mov_b32 s0, 0x3fb8aa3b
	v_fma_f32 v6, v2, s0, -v5
	v_rndne_f32_e32 v7, v5
	v_fmac_f32_e32 v6, 0x32a5705f, v2
	v_sub_f32_e32 v5, v5, v7
	v_add_f32_e32 v5, v5, v6
	v_exp_f32_e32 v5, v5
	v_cvt_i32_f32_e32 v6, v7
	s_mov_b32 s0, 0xc2ce8ed0
	v_cmp_ngt_f32_e32 vcc, s0, v2
	s_mov_b32 s0, 0x42b17218
	v_ldexp_f32 v5, v5, v6
	v_cndmask_b32_e32 v5, 0, v5, vcc
	v_cmp_nlt_f32_e32 vcc, s0, v2
	v_xor_b32_e32 v1, v1, v0
	s_movk_i32 s0, 0x1f8
	v_cndmask_b32_e32 v2, v226, v5, vcc
	v_mul_f32_e32 v5, v3, v3
	v_fmamk_f32 v6, v5, 0xb94c1982, v219
	v_fmaak_f32 v6, v5, v6, 0xbe2aaa9d
	v_mul_f32_e32 v6, v5, v6
	v_fmac_f32_e32 v3, v3, v6
	v_fmamk_f32 v6, v5, 0x37d75334, v220
	v_fmaak_f32 v6, v5, v6, 0x3d2aabf7
	v_fmaak_f32 v6, v5, v6, 0xbf000004
	v_fma_f32 v5, v5, v6, 1.0
	v_lshlrev_b32_e32 v6, 30, v4
	v_and_b32_e32 v4, 1, v4
	v_cmp_eq_u32_e32 vcc, 0, v4
	v_and_b32_e32 v6, 0x80000000, v6
	v_ashrrev_i32_e32 v33, 31, v32
	v_cndmask_b32_e32 v4, v5, v3, vcc
	v_xor_b32_e32 v3, 0x80000000, v3
	v_xor_b32_e32 v1, v1, v4
	v_cndmask_b32_e32 v3, v3, v5, vcc
	v_cmp_class_f32_e64 vcc, v0, s0
	v_xor_b32_e32 v0, v1, v6
	v_xor_b32_e32 v3, v3, v6
	v_cndmask_b32_e32 v1, v229, v0, vcc
	v_cndmask_b32_e32 v0, v229, v3, vcc
	v_pk_mul_f32 v[34:35], v[2:3], v[0:1] op_sel_hi:[0,1]
	v_pk_mul_f32 v[0:1], v[36:37], v[36:37]
	v_readlane_b32 s4, v250, 50
	v_add_f32_e32 v0, v0, v1
	v_div_scale_f32 v1, s[0:1], v0, v0, 1.0
	v_rcp_f32_e32 v2, v1
	v_readlane_b32 s0, v255, 0
	v_readlane_b32 s1, v255, 1
	v_readlane_b32 s8, v250, 54
	v_fma_f32 v3, -v1, v2, 1.0
	v_fmac_f32_e32 v2, v3, v2
	v_div_scale_f32 v3, vcc, 1.0, v0, 1.0
	v_mul_f32_e32 v4, v3, v2
	v_fma_f32 v5, -v1, v4, v3
	v_fmac_f32_e32 v4, v5, v2
	v_fma_f32 v1, -v1, v4, v3
	v_div_fmas_f32 v1, v1, v2, v4
	v_div_fixup_f32 v40, v1, v0, 1.0
	v_lshl_add_u64 v[0:1], v[32:33], 4, s[0:1]
	v_lshlrev_b64 v[0:1], 2, v[0:1]
	v_readlane_b32 s9, v250, 55
	v_readlane_b32 s10, v250, 56
	v_readlane_b32 s11, v250, 57
	v_lshl_add_u64 v[4:5], s[8:9], 0, v[0:1]
	v_add_f32_e32 v38, -1.0, v34
	v_lshl_add_u64 v[28:29], s[10:11], 0, v[0:1]
	global_load_dwordx4 v[0:3], v[4:5], off offset:48
	global_load_dwordx4 v[8:11], v[4:5], off offset:32
	global_load_dwordx4 v[16:19], v[4:5], off offset:16
	global_load_dwordx4 v[24:27], v[4:5], off
	s_nop 0
	global_load_dwordx4 v[4:7], v[28:29], off offset:48
	global_load_dwordx4 v[12:15], v[28:29], off offset:32
	global_load_dwordx4 v[20:23], v[28:29], off offset:16
	s_nop 0
	global_load_dwordx4 v[28:31], v[28:29], off
	v_mov_b32_e32 v42, v37
	v_mov_b32_e32 v44, v35
	v_mov_b32_e32 v45, v38
	v_mov_b32_e32 v39, v35
	v_pk_mul_f32 v[42:43], v[42:43], v[44:45] op_sel_hi:[0,1]
	v_pk_fma_f32 v[44:45], v[36:37], v[38:39], v[42:43]
	v_pk_fma_f32 v[36:37], v[36:37], v[38:39], v[42:43] op_sel_hi:[0,1,1] neg_lo:[0,0,1] neg_hi:[0,0,1]
	v_mov_b32_e32 v45, v37
	v_pk_mul_f32 v[44:45], v[40:41], v[44:45] op_sel_hi:[0,1]
	v_readlane_b32 s0, v252, 6
	v_readlane_b32 s1, v252, 7
	v_pk_mov_b32 v[46:47], v[34:35], v[34:35] op_sel:[1,0]
	v_readlane_b32 s5, v250, 51
	v_readlane_b32 s6, v250, 52
	v_readlane_b32 s7, v250, 53
	v_readlane_b32 s12, v250, 58
	v_readlane_b32 s13, v250, 59
	v_readlane_b32 s14, v250, 60
	v_readlane_b32 s15, v250, 61
	v_readlane_b32 s16, v250, 62
	v_readlane_b32 s17, v250, 63
	v_readlane_b32 s18, v251, 0
	v_readlane_b32 s19, v251, 1
	s_waitcnt vmcnt(0)
	v_pk_mul_f32 v[38:39], v[28:29], v[44:45] op_sel:[0,1] op_sel_hi:[0,0]
	v_pk_fma_f32 v[36:37], v[24:25], v[44:45], v[38:39] neg_lo:[0,0,1] neg_hi:[0,0,1]
	v_pk_fma_f32 v[38:39], v[24:25], v[44:45], v[38:39] op_sel_hi:[0,1,1]
	v_mov_b32_e32 v37, v39
	v_pk_mul_f32 v[38:39], v[28:29], v[44:45] op_sel:[1,1] op_sel_hi:[1,0]
	v_mov_b32_e32 v28, v25
	v_pk_fma_f32 v[28:29], v[28:29], v[44:45], v[38:39] neg_lo:[0,0,1] neg_hi:[0,0,1]
	v_pk_fma_f32 v[24:25], v[24:25], v[44:45], v[38:39] op_sel:[1,0,0]
	v_pk_mul_f32 v[38:39], v[30:31], v[44:45] op_sel:[0,1] op_sel_hi:[0,0]
	v_mov_b32_e32 v29, v25
	v_pk_fma_f32 v[24:25], v[26:27], v[44:45], v[38:39] neg_lo:[0,0,1] neg_hi:[0,0,1]
	v_pk_fma_f32 v[38:39], v[26:27], v[44:45], v[38:39] op_sel_hi:[0,1,1]
	v_mov_b32_e32 v26, v31
	v_pk_mul_f32 v[30:31], v[26:27], v[44:45] op_sel:[0,1] op_sel_hi:[0,0]
	v_mov_b32_e32 v26, v27
	v_mov_b32_e32 v38, v27
	v_mov_b32_e32 v25, v39
	v_pk_fma_f32 v[26:27], v[26:27], v[44:45], v[30:31] neg_lo:[0,0,1] neg_hi:[0,0,1]
	v_pk_fma_f32 v[30:31], v[38:39], v[44:45], v[30:31] op_sel_hi:[0,1,1]
	v_pk_mul_f32 v[38:39], v[20:21], v[44:45] op_sel:[0,1] op_sel_hi:[0,0]
	v_mov_b32_e32 v27, v31
	v_pk_fma_f32 v[30:31], v[16:17], v[44:45], v[38:39] neg_lo:[0,0,1] neg_hi:[0,0,1]
	v_pk_fma_f32 v[38:39], v[16:17], v[44:45], v[38:39] op_sel_hi:[0,1,1]
	v_mov_b32_e32 v31, v39
	v_pk_mul_f32 v[38:39], v[44:45], v[20:21] op_sel:[1,1] op_sel_hi:[0,1]
	v_mov_b32_e32 v20, v17
	v_pk_fma_f32 v[20:21], v[20:21], v[44:45], v[38:39] neg_lo:[0,0,1] neg_hi:[0,0,1]
	v_pk_fma_f32 v[16:17], v[16:17], v[44:45], v[38:39] op_sel:[1,0,0]
	v_pk_mul_f32 v[38:39], v[44:45], v[22:23] op_sel:[1,0] op_sel_hi:[0,0]
	v_mov_b32_e32 v21, v17
	v_pk_fma_f32 v[16:17], v[18:19], v[44:45], v[38:39] neg_lo:[0,0,1] neg_hi:[0,0,1]
	v_pk_fma_f32 v[38:39], v[18:19], v[44:45], v[38:39] op_sel_hi:[0,1,1]
	v_mov_b32_e32 v18, v23
	v_pk_mul_f32 v[22:23], v[44:45], v[18:19] op_sel:[1,0] op_sel_hi:[0,0]
	v_mov_b32_e32 v18, v19
	v_mov_b32_e32 v38, v19
	v_mov_b32_e32 v17, v39
	v_pk_fma_f32 v[18:19], v[18:19], v[44:45], v[22:23] neg_lo:[0,0,1] neg_hi:[0,0,1]
	v_pk_fma_f32 v[22:23], v[38:39], v[44:45], v[22:23] op_sel_hi:[0,1,1]
	v_pk_mul_f32 v[38:39], v[44:45], v[12:13] op_sel:[1,0] op_sel_hi:[0,0]
; template <bool FINAL>
; __device__ __forceinline__ void s5_wave(const Params& P, int j, int g, int idx0, int stride, char* ldsw) {
;     ...
; #pragma unroll
;     for (int q = 0; q < 4; ++q) {
;       float4 a = br4[q], c = bi4[q];
;       bb[4 * q + 0] = (f32x2){cr * a.x - ci * c.x, cr * c.x + ci * a.x};
;       bb[4 * q + 1] = (f32x2){cr * a.y - ci * c.y, cr * c.y + ci * a.y};
;       bb[4 * q + 2] = (f32x2){cr * a.z - ci * c.z, cr * c.z + ci * a.z};
;       bb[4 * q + 3] = (f32x2){cr * a.w - ci * c.w, cr * c.w + ci * a.w};
;     }
;   }
;     ...
;   for (int idx = idx0; idx < 16384; idx += stride) {
;   const int b = idx >> 11, chunk = ((idx >> 5) + 8 * b) & 63;
;   const size_t rowbase = (size_t)b * 4096 + chunk * 64;
;   const u16* up = Zo + (rowbase + lane) * 1280 + 768 + g * 16;
;   const uint4 u0 = *reinterpret_cast<const uint4*>(up);
;   const uint4 u1 = *reinterpret_cast<const uint4*>(up + 8);
	v_mov_b32_e32 v19, v23
	v_pk_fma_f32 v[22:23], v[44:45], v[8:9], v[38:39] neg_lo:[0,0,1] neg_hi:[0,0,1]
	v_pk_fma_f32 v[38:39], v[44:45], v[8:9], v[38:39] op_sel_hi:[1,0,1]
	s_nop 0
	v_mov_b32_e32 v23, v39
	v_pk_mul_f32 v[38:39], v[44:45], v[12:13] op_sel:[1,1] op_sel_hi:[0,1]
	v_mov_b32_e32 v12, v9
	v_pk_fma_f32 v[12:13], v[44:45], v[12:13], v[38:39] neg_lo:[0,0,1] neg_hi:[0,0,1]
	v_pk_fma_f32 v[8:9], v[44:45], v[8:9], v[38:39] op_sel:[0,1,0]
	v_pk_mul_f32 v[38:39], v[44:45], v[14:15] op_sel:[1,0] op_sel_hi:[0,0]
	v_mov_b32_e32 v13, v9
	v_pk_fma_f32 v[8:9], v[44:45], v[10:11], v[38:39] neg_lo:[0,0,1] neg_hi:[0,0,1]
	v_pk_fma_f32 v[38:39], v[44:45], v[10:11], v[38:39] op_sel_hi:[1,0,1]
	v_mov_b32_e32 v10, v15
	v_pk_mul_f32 v[14:15], v[44:45], v[10:11] op_sel:[1,0] op_sel_hi:[0,0]
	v_mov_b32_e32 v10, v11
	v_mov_b32_e32 v38, v11
	v_mov_b32_e32 v9, v39
	v_pk_fma_f32 v[10:11], v[44:45], v[10:11], v[14:15] neg_lo:[0,0,1] neg_hi:[0,0,1]
	v_pk_fma_f32 v[14:15], v[44:45], v[38:39], v[14:15] op_sel_hi:[1,0,1]
	v_pk_mul_f32 v[38:39], v[44:45], v[4:5] op_sel:[1,0] op_sel_hi:[0,0]
	v_mov_b32_e32 v11, v15
	v_pk_fma_f32 v[14:15], v[44:45], v[0:1], v[38:39] neg_lo:[0,0,1] neg_hi:[0,0,1]
	v_pk_fma_f32 v[38:39], v[44:45], v[0:1], v[38:39] op_sel_hi:[1,0,1]
	v_pk_mul_f32 v[4:5], v[44:45], v[4:5] op_sel:[1,1] op_sel_hi:[0,1]
	v_mov_b32_e32 v38, v1
	v_mov_b32_e32 v15, v39
	v_pk_fma_f32 v[38:39], v[44:45], v[38:39], v[4:5] neg_lo:[0,0,1] neg_hi:[0,0,1]
	v_pk_fma_f32 v[0:1], v[44:45], v[0:1], v[4:5] op_sel:[0,1,0]
	v_mov_b32_e32 v4, v3
	v_mov_b32_e32 v39, v1
	v_pk_mul_f32 v[0:1], v[44:45], v[6:7] op_sel:[1,0] op_sel_hi:[0,0]
	v_pk_fma_f32 v[40:41], v[44:45], v[2:3], v[0:1] neg_lo:[0,0,1] neg_hi:[0,0,1]
	v_pk_fma_f32 v[0:1], v[44:45], v[2:3], v[0:1] op_sel_hi:[1,0,1]
	v_mov_b32_e32 v2, v3
	v_mov_b32_e32 v0, v7
	v_mov_b32_e32 v41, v1
	v_pk_mul_f32 v[0:1], v[44:45], v[0:1] op_sel:[1,0] op_sel_hi:[0,0]
	v_pk_fma_f32 v[42:43], v[44:45], v[2:3], v[0:1] neg_lo:[0,0,1] neg_hi:[0,0,1]
	v_pk_fma_f32 v[0:1], v[44:45], v[4:5], v[0:1] op_sel_hi:[1,0,1]
	v_lshl_add_u64 v[44:45], v[32:33], 3, s[0:1]
	v_readlane_b32 s0, v251, 22
	v_mov_b32_e32 v43, v1
	s_mov_b32 s2, s0
	v_readlane_b32 s1, v251, 23
	v_and_b32_e32 v109, 31, v32
	v_mul_u32_u24_e32 v110, 0xa00, v109
	v_mov_b32_e32 v111, 0
	v_cmp_gt_u32_e32 vcc, 32, v32
	s_nop 1
	v_cndmask_b32_e64 v108, 0, 16, vcc
	v_permlane32_swap_b32_e32 v36, v28
	v_permlane32_swap_b32_e32 v37, v29
	v_permlane32_swap_b32_e32 v24, v26
	v_permlane32_swap_b32_e32 v25, v27
	v_permlane32_swap_b32_e32 v30, v20
	v_permlane32_swap_b32_e32 v31, v21
	v_permlane32_swap_b32_e32 v16, v18
	v_permlane32_swap_b32_e32 v17, v19
	v_permlane32_swap_b32_e32 v22, v12
	v_permlane32_swap_b32_e32 v23, v13
	v_permlane32_swap_b32_e32 v8, v10
	v_permlane32_swap_b32_e32 v9, v11
	v_permlane32_swap_b32_e32 v14, v38
	v_permlane32_swap_b32_e32 v15, v39
	v_permlane32_swap_b32_e32 v40, v42
	v_permlane32_swap_b32_e32 v41, v43
	v_readlane_b32 s1, v252, 1
	s_lshl_b32 s1, s1, 1
	s_add_u32 s5, s1, 0x17840600
	s_ashr_i32 s0, s2, 11
	s_lshr_b32 s1, s2, 5
	s_lshl_b32 s4, s0, 3
	s_add_i32 s4, s4, s1
	s_and_b32 s4, s4, 63
	s_lshl_b32 s6, s0, 12
	s_lshl_b32 s7, s4, 6
	s_or_b32 s6, s6, s7
	s_mul_i32 s6, s6, 0xa00
	s_add_u32 s6, s6, s5
	s_add_u32 s8, s90, s6
	s_addc_u32 s9, s91, 0
	v_lshl_add_u64 v[64:65], v[110:111], 0, s[8:9]
	global_load_dwordx4 v[0:3], v[64:65], off
	global_load_dwordx4 v[4:7], v[64:65], off offset:16
	global_load_dword v68, v[64:65], off
.Ls5p1_job:
	s_ashr_i32 s0, s2, 11
	s_lshr_b32 s1, s2, 5
	s_lshl_b32 s4, s0, 3
	s_add_i32 s4, s4, s1
	s_and_b32 s4, s4, 63
	s_lshl_b32 s6, s0, 12
	s_lshl_b32 s7, s4, 6
	s_or_b32 s6, s6, s7
	s_mul_i32 s6, s6, 0xa00
	s_add_u32 s6, s6, s5
	s_add_u32 s8, s90, s6
	s_addc_u32 s9, s91, 0
	s_add_u32 s10, s8, 0x14000
	s_addc_u32 s11, s9, 0
	v_lshl_add_u64 v[64:65], v[110:111], 0, s[10:11]
	global_load_dwordx4 v[56:59], v[64:65], off
	global_load_dwordx4 v[60:63], v[64:65], off offset:16
	s_lshl_b32 s14, s0, 6
	s_or_b32 s14, s4, s14
	s_ashr_i32 s15, s14, 31
	s_lshl_b64 s[14:15], s[14:15], 14
	v_lshl_add_u64 v[66:67], v[44:45], 0, s[14:15]
	v_readlane_b32 s17, v251, 20
	s_add_i32 s17, s2, s17
	s_cmpk_gt_i32 s17, 0x3fff
	s_cselect_b32 s17, s2, s17
	s_ashr_i32 s0, s17, 11
	s_lshr_b32 s1, s17, 5
	s_lshl_b32 s4, s0, 3
	s_add_i32 s4, s4, s1
	s_and_b32 s4, s4, 63
	s_lshl_b32 s6, s0, 12
	s_lshl_b32 s7, s4, 6
	s_or_b32 s6, s6, s7
	s_mul_i32 s6, s6, 0xa00
	s_add_u32 s6, s6, s5
	s_add_u32 s10, s90, s6
	s_addc_u32 s11, s91, 0
	v_mov_b32_e32 v54, 0
	v_mov_b32_e32 v55, 0
	s_waitcnt vmcnt(3)
; template <bool FINAL>
; __device__ __forceinline__ void s5_wave(const Params& P, int j, int g, int idx0, int stride, char* ldsw) {
;     ...
; #pragma unroll 2
;   for (int t = 0; t < 64; ++t) {
;     uint32_t w[8];
;     w[0] = __builtin_amdgcn_readlane(u0.x, t); w[1] = __builtin_amdgcn_readlane(u0.y, t);
;     w[2] = __builtin_amdgcn_readlane(u0.z, t); w[3] = __builtin_amdgcn_readlane(u0.w, t);
;     w[4] = __builtin_amdgcn_readlane(u1.x, t); w[5] = __builtin_amdgcn_readlane(u1.y, t);
;     w[6] = __builtin_amdgcn_readlane(u1.z, t); w[7] = __builtin_amdgcn_readlane(u1.w, t);
;     f32x2 acc0 = (f32x2){lbr * hr - lbi * hi, lbr * hi + lbi * hr}, acc1 = (f32x2){0.f, 0.f};
; #pragma unroll
;     for (int q = 0; q < 8; ++q) {
;       float ua = __uint_as_float(w[q] << 16), ub = __uint_as_float(w[q] & 0xffff0000u);
;       acc0 = bb[2 * q] * (f32x2){ua, ua} + acc0;
;       acc1 = bb[2 * q + 1] * (f32x2){ub, ub} + acc1;
;     }
;     acc0 = acc0 + acc1;
;     hr = acc0.x; hi = acc0.y;
;     if (FINAL) hbuf[t * 68 + p] = pack2(hr, hi);
;   }
	v_lshlrev_b32_e32 v100, v108, v0
	v_lshlrev_b32_e32 v101, v108, v1
	v_lshlrev_b32_e32 v102, v108, v2
	v_lshlrev_b32_e32 v103, v108, v3
	v_lshlrev_b32_e32 v104, v108, v4
	v_lshlrev_b32_e32 v105, v108, v5
	v_lshlrev_b32_e32 v106, v108, v6
	v_lshlrev_b32_e32 v107, v108, v7
	v_and_b32_e32 v100, 0xffff0000, v100
	v_and_b32_e32 v101, 0xffff0000, v101
	v_and_b32_e32 v102, 0xffff0000, v102
	v_and_b32_e32 v103, 0xffff0000, v103
	v_and_b32_e32 v104, 0xffff0000, v104
	v_and_b32_e32 v105, 0xffff0000, v105
	v_and_b32_e32 v106, 0xffff0000, v106
	v_and_b32_e32 v107, 0xffff0000, v107
	v_lshl_add_u64 v[64:65], v[110:111], 0, s[10:11]
	global_load_dwordx4 v[0:3], v[64:65], off
	global_load_dwordx4 v[4:7], v[64:65], off offset:16
	v_mfma_f32_32x32x2_f32 v[116:131], v100, v36, 0
	v_mfma_f32_32x32x2_f32 v[132:147], v100, v37, 0
	v_mfma_f32_32x32x2_f32 v[148:163], v100, v28, 0
	v_mfma_f32_32x32x2_f32 v[164:179], v100, v29, 0
	v_mfma_f32_32x32x2_f32 v[116:131], v101, v24, v[116:131]
	v_mfma_f32_32x32x2_f32 v[132:147], v101, v25, v[132:147]
	v_mfma_f32_32x32x2_f32 v[148:163], v101, v26, v[148:163]
	v_mfma_f32_32x32x2_f32 v[164:179], v101, v27, v[164:179]
	v_mfma_f32_32x32x2_f32 v[116:131], v102, v30, v[116:131]
	v_mfma_f32_32x32x2_f32 v[132:147], v102, v31, v[132:147]
	v_mfma_f32_32x32x2_f32 v[148:163], v102, v20, v[148:163]
	v_mfma_f32_32x32x2_f32 v[164:179], v102, v21, v[164:179]
	v_mfma_f32_32x32x2_f32 v[116:131], v103, v16, v[116:131]
	v_mfma_f32_32x32x2_f32 v[132:147], v103, v17, v[132:147]
	v_mfma_f32_32x32x2_f32 v[148:163], v103, v18, v[148:163]
	v_mfma_f32_32x32x2_f32 v[164:179], v103, v19, v[164:179]
	v_mfma_f32_32x32x2_f32 v[116:131], v104, v22, v[116:131]
	v_mfma_f32_32x32x2_f32 v[132:147], v104, v23, v[132:147]
	v_mfma_f32_32x32x2_f32 v[148:163], v104, v12, v[148:163]
	v_mfma_f32_32x32x2_f32 v[164:179], v104, v13, v[164:179]
	v_mfma_f32_32x32x2_f32 v[116:131], v105, v8, v[116:131]
	v_mfma_f32_32x32x2_f32 v[132:147], v105, v9, v[132:147]
	v_mfma_f32_32x32x2_f32 v[148:163], v105, v10, v[148:163]
	v_mfma_f32_32x32x2_f32 v[164:179], v105, v11, v[164:179]
	v_mfma_f32_32x32x2_f32 v[116:131], v106, v14, v[116:131]
	v_mfma_f32_32x32x2_f32 v[132:147], v106, v15, v[132:147]
	v_mfma_f32_32x32x2_f32 v[148:163], v106, v38, v[148:163]
	v_mfma_f32_32x32x2_f32 v[164:179], v106, v39, v[164:179]
	v_mfma_f32_32x32x2_f32 v[116:131], v107, v40, v[116:131]
	v_mfma_f32_32x32x2_f32 v[132:147], v107, v41, v[132:147]
	v_mfma_f32_32x32x2_f32 v[148:163], v107, v42, v[148:163]
	v_mfma_f32_32x32x2_f32 v[164:179], v107, v43, v[164:179]
	s_nop 15
	s_nop 3
	v_permlane32_swap_b32_e32 v116, v148
	v_permlane32_swap_b32_e32 v132, v164
	v_permlane32_swap_b32_e32 v117, v149
	v_permlane32_swap_b32_e32 v133, v165
	v_permlane32_swap_b32_e32 v118, v150
	v_permlane32_swap_b32_e32 v134, v166
	v_permlane32_swap_b32_e32 v119, v151
	v_permlane32_swap_b32_e32 v135, v167
	v_permlane32_swap_b32_e32 v120, v152
	v_permlane32_swap_b32_e32 v136, v168
	v_permlane32_swap_b32_e32 v121, v153
	v_permlane32_swap_b32_e32 v137, v169
	v_permlane32_swap_b32_e32 v122, v154
	v_permlane32_swap_b32_e32 v138, v170
	v_permlane32_swap_b32_e32 v123, v155
	v_permlane32_swap_b32_e32 v139, v171
	v_permlane32_swap_b32_e32 v124, v156
	v_permlane32_swap_b32_e32 v140, v172
	v_permlane32_swap_b32_e32 v125, v157
	v_permlane32_swap_b32_e32 v141, v173
	v_permlane32_swap_b32_e32 v126, v158
	v_permlane32_swap_b32_e32 v142, v174
	v_permlane32_swap_b32_e32 v127, v159
	v_permlane32_swap_b32_e32 v143, v175
	v_permlane32_swap_b32_e32 v128, v160
	v_permlane32_swap_b32_e32 v144, v176
	v_permlane32_swap_b32_e32 v129, v161
	v_permlane32_swap_b32_e32 v145, v177
	v_permlane32_swap_b32_e32 v130, v162
	v_permlane32_swap_b32_e32 v146, v178
	v_permlane32_swap_b32_e32 v131, v163
	v_permlane32_swap_b32_e32 v147, v179
	v_fma_f32 v116, v34, v54, v116
	v_fma_f32 v132, v34, v55, v132
	v_fma_f32 v116, -v35, v55, v116
	v_fma_f32 v132, v35, v54, v132
	v_fma_f32 v117, v34, v116, v117
	v_fma_f32 v133, v34, v132, v133
	v_fma_f32 v117, -v35, v132, v117
	v_fma_f32 v133, v35, v116, v133
	v_fma_f32 v118, v34, v117, v118
	v_fma_f32 v134, v34, v133, v134
	v_fma_f32 v118, -v35, v133, v118
	v_fma_f32 v134, v35, v117, v134
	v_fma_f32 v119, v34, v118, v119
	v_fma_f32 v135, v34, v134, v135
	v_fma_f32 v119, -v35, v134, v119
	v_fma_f32 v135, v35, v118, v135
	v_fma_f32 v148, v34, v119, v148
	v_fma_f32 v164, v34, v135, v164
	v_fma_f32 v148, -v35, v135, v148
	v_fma_f32 v164, v35, v119, v164
	v_fma_f32 v149, v34, v148, v149
	v_fma_f32 v165, v34, v164, v165
	v_fma_f32 v149, -v35, v164, v149
	v_fma_f32 v165, v35, v148, v165
	v_fma_f32 v150, v34, v149, v150
	v_fma_f32 v166, v34, v165, v166
	v_fma_f32 v150, -v35, v165, v150
	v_fma_f32 v166, v35, v149, v166
	v_fma_f32 v151, v34, v150, v151
	v_fma_f32 v167, v34, v166, v167
	v_fma_f32 v151, -v35, v166, v151
	v_fma_f32 v167, v35, v150, v167
	v_fma_f32 v120, v34, v151, v120
	v_fma_f32 v136, v34, v167, v136
	v_fma_f32 v120, -v35, v167, v120
	v_fma_f32 v136, v35, v151, v136
	v_fma_f32 v121, v34, v120, v121
	v_fma_f32 v137, v34, v136, v137
	v_fma_f32 v121, -v35, v136, v121
	v_fma_f32 v137, v35, v120, v137
	v_fma_f32 v122, v34, v121, v122
	v_fma_f32 v138, v34, v137, v138
	v_fma_f32 v122, -v35, v137, v122
	v_fma_f32 v138, v35, v121, v138
	v_fma_f32 v123, v34, v122, v123
	v_fma_f32 v139, v34, v138, v139
	v_fma_f32 v123, -v35, v138, v123
	v_fma_f32 v139, v35, v122, v139
	v_fma_f32 v152, v34, v123, v152
	v_fma_f32 v168, v34, v139, v168
	v_fma_f32 v152, -v35, v139, v152
	v_fma_f32 v168, v35, v123, v168
	v_fma_f32 v153, v34, v152, v153
	v_fma_f32 v169, v34, v168, v169
	v_fma_f32 v153, -v35, v168, v153
	v_fma_f32 v169, v35, v152, v169
; template <bool FINAL>
; __device__ __forceinline__ void s5_wave(const Params& P, int j, int g, int idx0, int stride, char* ldsw) {
;     ...
; #pragma unroll 2
;   for (int t = 0; t < 64; ++t) {
;     uint32_t w[8];
;     w[0] = __builtin_amdgcn_readlane(u0.x, t); w[1] = __builtin_amdgcn_readlane(u0.y, t);
;     w[2] = __builtin_amdgcn_readlane(u0.z, t); w[3] = __builtin_amdgcn_readlane(u0.w, t);
;     w[4] = __builtin_amdgcn_readlane(u1.x, t); w[5] = __builtin_amdgcn_readlane(u1.y, t);
;     w[6] = __builtin_amdgcn_readlane(u1.z, t); w[7] = __builtin_amdgcn_readlane(u1.w, t);
;     f32x2 acc0 = (f32x2){lbr * hr - lbi * hi, lbr * hi + lbi * hr}, acc1 = (f32x2){0.f, 0.f};
; #pragma unroll
;     for (int q = 0; q < 8; ++q) {
;       float ua = __uint_as_float(w[q] << 16), ub = __uint_as_float(w[q] & 0xffff0000u);
;       acc0 = bb[2 * q] * (f32x2){ua, ua} + acc0;
;       acc1 = bb[2 * q + 1] * (f32x2){ub, ub} + acc1;
;     }
;     acc0 = acc0 + acc1;
;     hr = acc0.x; hi = acc0.y;
;     if (FINAL) hbuf[t * 68 + p] = pack2(hr, hi);
;   }
	v_fma_f32 v154, v34, v153, v154
	v_fma_f32 v170, v34, v169, v170
	v_fma_f32 v154, -v35, v169, v154
	v_fma_f32 v170, v35, v153, v170
	v_fma_f32 v155, v34, v154, v155
	v_fma_f32 v171, v34, v170, v171
	v_fma_f32 v155, -v35, v170, v155
	v_fma_f32 v171, v35, v154, v171
	v_fma_f32 v124, v34, v155, v124
	v_fma_f32 v140, v34, v171, v140
	v_fma_f32 v124, -v35, v171, v124
	v_fma_f32 v140, v35, v155, v140
	v_fma_f32 v125, v34, v124, v125
	v_fma_f32 v141, v34, v140, v141
	v_fma_f32 v125, -v35, v140, v125
	v_fma_f32 v141, v35, v124, v141
	v_fma_f32 v126, v34, v125, v126
	v_fma_f32 v142, v34, v141, v142
	v_fma_f32 v126, -v35, v141, v126
	v_fma_f32 v142, v35, v125, v142
	v_fma_f32 v127, v34, v126, v127
	v_fma_f32 v143, v34, v142, v143
	v_fma_f32 v127, -v35, v142, v127
	v_fma_f32 v143, v35, v126, v143
	v_fma_f32 v156, v34, v127, v156
	v_fma_f32 v172, v34, v143, v172
	v_fma_f32 v156, -v35, v143, v156
	v_fma_f32 v172, v35, v127, v172
	v_fma_f32 v157, v34, v156, v157
	v_fma_f32 v173, v34, v172, v173
	v_fma_f32 v157, -v35, v172, v157
	v_fma_f32 v173, v35, v156, v173
	v_fma_f32 v158, v34, v157, v158
	v_fma_f32 v174, v34, v173, v174
	v_fma_f32 v158, -v35, v173, v158
	v_fma_f32 v174, v35, v157, v174
	v_fma_f32 v159, v34, v158, v159
	v_fma_f32 v175, v34, v174, v175
	v_fma_f32 v159, -v35, v174, v159
	v_fma_f32 v175, v35, v158, v175
	v_fma_f32 v128, v34, v159, v128
	v_fma_f32 v144, v34, v175, v144
	v_fma_f32 v128, -v35, v175, v128
	v_fma_f32 v144, v35, v159, v144
	v_fma_f32 v129, v34, v128, v129
	v_fma_f32 v145, v34, v144, v145
	v_fma_f32 v129, -v35, v144, v129
	v_fma_f32 v145, v35, v128, v145
	v_fma_f32 v130, v34, v129, v130
	v_fma_f32 v146, v34, v145, v146
	v_fma_f32 v130, -v35, v145, v130
	v_fma_f32 v146, v35, v129, v146
	v_fma_f32 v131, v34, v130, v131
	v_fma_f32 v147, v34, v146, v147
	v_fma_f32 v131, -v35, v146, v131
	v_fma_f32 v147, v35, v130, v147
	v_fma_f32 v160, v34, v131, v160
	v_fma_f32 v176, v34, v147, v176
	v_fma_f32 v160, -v35, v147, v160
	v_fma_f32 v176, v35, v131, v176
	v_fma_f32 v161, v34, v160, v161
	v_fma_f32 v177, v34, v176, v177
	v_fma_f32 v161, -v35, v176, v161
	v_fma_f32 v177, v35, v160, v177
	v_fma_f32 v162, v34, v161, v162
	v_fma_f32 v178, v34, v177, v178
	v_fma_f32 v162, -v35, v177, v162
	v_fma_f32 v178, v35, v161, v178
	v_fma_f32 v163, v34, v162, v163
	v_fma_f32 v179, v34, v178, v179
	v_fma_f32 v163, -v35, v178, v163
	v_fma_f32 v179, v35, v162, v179
	v_mov_b32_e32 v54, v163
	v_mov_b32_e32 v55, v179
	s_waitcnt vmcnt(2)
	v_lshlrev_b32_e32 v100, v108, v56
	v_lshlrev_b32_e32 v101, v108, v57
	v_lshlrev_b32_e32 v102, v108, v58
	v_lshlrev_b32_e32 v103, v108, v59
	v_lshlrev_b32_e32 v104, v108, v60
	v_lshlrev_b32_e32 v105, v108, v61
	v_lshlrev_b32_e32 v106, v108, v62
	v_lshlrev_b32_e32 v107, v108, v63
	v_and_b32_e32 v100, 0xffff0000, v100
	v_and_b32_e32 v101, 0xffff0000, v101
	v_and_b32_e32 v102, 0xffff0000, v102
	v_and_b32_e32 v103, 0xffff0000, v103
	v_and_b32_e32 v104, 0xffff0000, v104
	v_and_b32_e32 v105, 0xffff0000, v105
	v_and_b32_e32 v106, 0xffff0000, v106
	v_and_b32_e32 v107, 0xffff0000, v107
	v_mfma_f32_32x32x2_f32 v[116:131], v100, v36, 0
	v_mfma_f32_32x32x2_f32 v[132:147], v100, v37, 0
	v_mfma_f32_32x32x2_f32 v[148:163], v100, v28, 0
	v_mfma_f32_32x32x2_f32 v[164:179], v100, v29, 0
	v_mfma_f32_32x32x2_f32 v[116:131], v101, v24, v[116:131]
	v_mfma_f32_32x32x2_f32 v[132:147], v101, v25, v[132:147]
	v_mfma_f32_32x32x2_f32 v[148:163], v101, v26, v[148:163]
	v_mfma_f32_32x32x2_f32 v[164:179], v101, v27, v[164:179]
	v_mfma_f32_32x32x2_f32 v[116:131], v102, v30, v[116:131]
	v_mfma_f32_32x32x2_f32 v[132:147], v102, v31, v[132:147]
	v_mfma_f32_32x32x2_f32 v[148:163], v102, v20, v[148:163]
	v_mfma_f32_32x32x2_f32 v[164:179], v102, v21, v[164:179]
	v_mfma_f32_32x32x2_f32 v[116:131], v103, v16, v[116:131]
	v_mfma_f32_32x32x2_f32 v[132:147], v103, v17, v[132:147]
	v_mfma_f32_32x32x2_f32 v[148:163], v103, v18, v[148:163]
	v_mfma_f32_32x32x2_f32 v[164:179], v103, v19, v[164:179]
	v_mfma_f32_32x32x2_f32 v[116:131], v104, v22, v[116:131]
	v_mfma_f32_32x32x2_f32 v[132:147], v104, v23, v[132:147]
	v_mfma_f32_32x32x2_f32 v[148:163], v104, v12, v[148:163]
	v_mfma_f32_32x32x2_f32 v[164:179], v104, v13, v[164:179]
	v_mfma_f32_32x32x2_f32 v[116:131], v105, v8, v[116:131]
	v_mfma_f32_32x32x2_f32 v[132:147], v105, v9, v[132:147]
	v_mfma_f32_32x32x2_f32 v[148:163], v105, v10, v[148:163]
	v_mfma_f32_32x32x2_f32 v[164:179], v105, v11, v[164:179]
	v_mfma_f32_32x32x2_f32 v[116:131], v106, v14, v[116:131]
	v_mfma_f32_32x32x2_f32 v[132:147], v106, v15, v[132:147]
	v_mfma_f32_32x32x2_f32 v[148:163], v106, v38, v[148:163]
	v_mfma_f32_32x32x2_f32 v[164:179], v106, v39, v[164:179]
	v_mfma_f32_32x32x2_f32 v[116:131], v107, v40, v[116:131]
	v_mfma_f32_32x32x2_f32 v[132:147], v107, v41, v[132:147]
	v_mfma_f32_32x32x2_f32 v[148:163], v107, v42, v[148:163]
	v_mfma_f32_32x32x2_f32 v[164:179], v107, v43, v[164:179]
	s_nop 15
	s_nop 3
	v_permlane32_swap_b32_e32 v116, v148
	v_permlane32_swap_b32_e32 v132, v164
	v_permlane32_swap_b32_e32 v117, v149
	v_permlane32_swap_b32_e32 v133, v165
	v_permlane32_swap_b32_e32 v118, v150
	v_permlane32_swap_b32_e32 v134, v166
	v_permlane32_swap_b32_e32 v119, v151
	v_permlane32_swap_b32_e32 v135, v167
	v_permlane32_swap_b32_e32 v120, v152
	v_permlane32_swap_b32_e32 v136, v168
	v_permlane32_swap_b32_e32 v121, v153
; template <bool FINAL>
; __device__ __forceinline__ void s5_wave(const Params& P, int j, int g, int idx0, int stride, char* ldsw) {
;     ...
; #pragma unroll 2
;   for (int t = 0; t < 64; ++t) {
;     uint32_t w[8];
;     w[0] = __builtin_amdgcn_readlane(u0.x, t); w[1] = __builtin_amdgcn_readlane(u0.y, t);
;     w[2] = __builtin_amdgcn_readlane(u0.z, t); w[3] = __builtin_amdgcn_readlane(u0.w, t);
;     w[4] = __builtin_amdgcn_readlane(u1.x, t); w[5] = __builtin_amdgcn_readlane(u1.y, t);
;     w[6] = __builtin_amdgcn_readlane(u1.z, t); w[7] = __builtin_amdgcn_readlane(u1.w, t);
;     f32x2 acc0 = (f32x2){lbr * hr - lbi * hi, lbr * hi + lbi * hr}, acc1 = (f32x2){0.f, 0.f};
; #pragma unroll
;     for (int q = 0; q < 8; ++q) {
;       float ua = __uint_as_float(w[q] << 16), ub = __uint_as_float(w[q] & 0xffff0000u);
;       acc0 = bb[2 * q] * (f32x2){ua, ua} + acc0;
;       acc1 = bb[2 * q + 1] * (f32x2){ub, ub} + acc1;
;     }
;     acc0 = acc0 + acc1;
;     hr = acc0.x; hi = acc0.y;
;     if (FINAL) hbuf[t * 68 + p] = pack2(hr, hi);
;   }
;   if (!FINAL) {
;     hend[((size_t)(b * 64 + chunk) * 32 + g) * 64 + p] = make_float2(hr, hi);
	v_permlane32_swap_b32_e32 v137, v169
	v_permlane32_swap_b32_e32 v122, v154
	v_permlane32_swap_b32_e32 v138, v170
	v_permlane32_swap_b32_e32 v123, v155
	v_permlane32_swap_b32_e32 v139, v171
	v_permlane32_swap_b32_e32 v124, v156
	v_permlane32_swap_b32_e32 v140, v172
	v_permlane32_swap_b32_e32 v125, v157
	v_permlane32_swap_b32_e32 v141, v173
	v_permlane32_swap_b32_e32 v126, v158
	v_permlane32_swap_b32_e32 v142, v174
	v_permlane32_swap_b32_e32 v127, v159
	v_permlane32_swap_b32_e32 v143, v175
	v_permlane32_swap_b32_e32 v128, v160
	v_permlane32_swap_b32_e32 v144, v176
	v_permlane32_swap_b32_e32 v129, v161
	v_permlane32_swap_b32_e32 v145, v177
	v_permlane32_swap_b32_e32 v130, v162
	v_permlane32_swap_b32_e32 v146, v178
	v_permlane32_swap_b32_e32 v131, v163
	v_permlane32_swap_b32_e32 v147, v179
	v_fma_f32 v116, v34, v54, v116
	v_fma_f32 v132, v34, v55, v132
	v_fma_f32 v116, -v35, v55, v116
	v_fma_f32 v132, v35, v54, v132
	v_fma_f32 v117, v34, v116, v117
	v_fma_f32 v133, v34, v132, v133
	v_fma_f32 v117, -v35, v132, v117
	v_fma_f32 v133, v35, v116, v133
	v_fma_f32 v118, v34, v117, v118
	v_fma_f32 v134, v34, v133, v134
	v_fma_f32 v118, -v35, v133, v118
	v_fma_f32 v134, v35, v117, v134
	v_fma_f32 v119, v34, v118, v119
	v_fma_f32 v135, v34, v134, v135
	v_fma_f32 v119, -v35, v134, v119
	v_fma_f32 v135, v35, v118, v135
	v_fma_f32 v148, v34, v119, v148
	v_fma_f32 v164, v34, v135, v164
	v_fma_f32 v148, -v35, v135, v148
	v_fma_f32 v164, v35, v119, v164
	v_fma_f32 v149, v34, v148, v149
	v_fma_f32 v165, v34, v164, v165
	v_fma_f32 v149, -v35, v164, v149
	v_fma_f32 v165, v35, v148, v165
	v_fma_f32 v150, v34, v149, v150
	v_fma_f32 v166, v34, v165, v166
	v_fma_f32 v150, -v35, v165, v150
	v_fma_f32 v166, v35, v149, v166
	v_fma_f32 v151, v34, v150, v151
	v_fma_f32 v167, v34, v166, v167
	v_fma_f32 v151, -v35, v166, v151
	v_fma_f32 v167, v35, v150, v167
	v_fma_f32 v120, v34, v151, v120
	v_fma_f32 v136, v34, v167, v136
	v_fma_f32 v120, -v35, v167, v120
	v_fma_f32 v136, v35, v151, v136
	v_fma_f32 v121, v34, v120, v121
	v_fma_f32 v137, v34, v136, v137
	v_fma_f32 v121, -v35, v136, v121
	v_fma_f32 v137, v35, v120, v137
	v_fma_f32 v122, v34, v121, v122
	v_fma_f32 v138, v34, v137, v138
	v_fma_f32 v122, -v35, v137, v122
	v_fma_f32 v138, v35, v121, v138
	v_fma_f32 v123, v34, v122, v123
	v_fma_f32 v139, v34, v138, v139
	v_fma_f32 v123, -v35, v138, v123
	v_fma_f32 v139, v35, v122, v139
	v_fma_f32 v152, v34, v123, v152
	v_fma_f32 v168, v34, v139, v168
	v_fma_f32 v152, -v35, v139, v152
	v_fma_f32 v168, v35, v123, v168
	v_fma_f32 v153, v34, v152, v153
	v_fma_f32 v169, v34, v168, v169
	v_fma_f32 v153, -v35, v168, v153
	v_fma_f32 v169, v35, v152, v169
	v_fma_f32 v154, v34, v153, v154
	v_fma_f32 v170, v34, v169, v170
	v_fma_f32 v154, -v35, v169, v154
	v_fma_f32 v170, v35, v153, v170
	v_fma_f32 v155, v34, v154, v155
	v_fma_f32 v171, v34, v170, v171
	v_fma_f32 v155, -v35, v170, v155
	v_fma_f32 v171, v35, v154, v171
	v_fma_f32 v124, v34, v155, v124
	v_fma_f32 v140, v34, v171, v140
	v_fma_f32 v124, -v35, v171, v124
	v_fma_f32 v140, v35, v155, v140
	v_fma_f32 v125, v34, v124, v125
	v_fma_f32 v141, v34, v140, v141
	v_fma_f32 v125, -v35, v140, v125
	v_fma_f32 v141, v35, v124, v141
	v_fma_f32 v126, v34, v125, v126
	v_fma_f32 v142, v34, v141, v142
	v_fma_f32 v126, -v35, v141, v126
	v_fma_f32 v142, v35, v125, v142
	v_fma_f32 v127, v34, v126, v127
	v_fma_f32 v143, v34, v142, v143
	v_fma_f32 v127, -v35, v142, v127
	v_fma_f32 v143, v35, v126, v143
	v_fma_f32 v156, v34, v127, v156
	v_fma_f32 v172, v34, v143, v172
	v_fma_f32 v156, -v35, v143, v156
	v_fma_f32 v172, v35, v127, v172
	v_fma_f32 v157, v34, v156, v157
	v_fma_f32 v173, v34, v172, v173
	v_fma_f32 v157, -v35, v172, v157
	v_fma_f32 v173, v35, v156, v173
	v_fma_f32 v158, v34, v157, v158
	v_fma_f32 v174, v34, v173, v174
	v_fma_f32 v158, -v35, v173, v158
	v_fma_f32 v174, v35, v157, v174
	v_fma_f32 v159, v34, v158, v159
	v_fma_f32 v175, v34, v174, v175
	v_fma_f32 v159, -v35, v174, v159
	v_fma_f32 v175, v35, v158, v175
	v_fma_f32 v128, v34, v159, v128
	v_fma_f32 v144, v34, v175, v144
	v_fma_f32 v128, -v35, v175, v128
	v_fma_f32 v144, v35, v159, v144
	v_fma_f32 v129, v34, v128, v129
	v_fma_f32 v145, v34, v144, v145
	v_fma_f32 v129, -v35, v144, v129
	v_fma_f32 v145, v35, v128, v145
	v_fma_f32 v130, v34, v129, v130
	v_fma_f32 v146, v34, v145, v146
	v_fma_f32 v130, -v35, v145, v130
	v_fma_f32 v146, v35, v129, v146
	v_fma_f32 v131, v34, v130, v131
	v_fma_f32 v147, v34, v146, v147
	v_fma_f32 v131, -v35, v146, v131
	v_fma_f32 v147, v35, v130, v147
	v_fma_f32 v160, v34, v131, v160
	v_fma_f32 v176, v34, v147, v176
	v_fma_f32 v160, -v35, v147, v160
	v_fma_f32 v176, v35, v131, v176
	v_fma_f32 v161, v34, v160, v161
	v_fma_f32 v177, v34, v176, v177
	v_fma_f32 v161, -v35, v176, v161
	v_fma_f32 v177, v35, v160, v177
	v_fma_f32 v162, v34, v161, v162
	v_fma_f32 v178, v34, v177, v178
	v_fma_f32 v162, -v35, v177, v162
	v_fma_f32 v178, v35, v161, v178
	v_fma_f32 v163, v34, v162, v163
	v_fma_f32 v179, v34, v178, v179
	v_fma_f32 v163, -v35, v178, v163
	v_fma_f32 v179, v35, v162, v179
	v_mov_b32_e32 v54, v163
	v_mov_b32_e32 v55, v179
	global_store_dwordx2 v[66:67], v[54:55], off
	v_readlane_b32 s0, v251, 20
	s_add_i32 s2, s2, s0
	s_cmpk_gt_i32 s2, 0x3fff
	s_cbranch_scc0 .Ls5p1_job
	s_waitcnt vmcnt(0)
